# aligned combo12 with arrival-rank-dependent background-conversion delay: the last six arrivers of an XCC start converting at once, the others keep the 2x64 delay
# baseline (speedup 1.0000x reference)
; __device__ __forceinline__ unsigned xb_add(unsigned* p, unsigned v) { return __hip_atomic_fetch_add(p, v, __ATOMIC_RELAXED, __HIP_MEMORY_SCOPE_AGENT); }
; __device__ __forceinline__ void xcd_barrier_thread0(const XcdBarrier& b) {
;     ...
;         unsigned nloc = b.st[0], nx = b.st[1];
;         if (nloc == 0u) { unsigned bal; xcd_barrier_complete(bar, b.x, nloc, nx, bal); b.st[0] = nloc; b.st[1] = nx; b.st[3] = bal; }
;         const unsigned old = xb_add(&bar[XB_XSUB(b.x)], 1u);
;         const unsigned gen = old / nloc;
;         if (old + 1u == (gen + 1u) * nloc) {
; __device__ __forceinline__ void xcc_barrier_thread0(const XcdBarrier& b) {
;     ...
;     const unsigned nloc = b.st[0];
;     const unsigned old = xb_add(&bar[XL_SUB(b.x)], 1u);
;     const unsigned gen = old / nloc;
;     if (old + 1u == (gen + 1u) * nloc) xb_add(&bar[XL_GEN(b.x)], 1u);
.LBB0_721:
	s_or_b64 exec, exec, s[0:1]
	v_cvt_f32_u32_e32 v7, v5
	s_waitcnt vmcnt(0)
	v_readfirstlane_b32 s0, v6
	s_and_b32 s8, s0, 31
	s_cmp_lt_u32 s8, 26
	s_cbranch_scc1 .Lbgd_w0skip
	s_add_i32 s8, s89, 1
	v_mov_b32_e32 v20, 0x20180
	v_mov_b32_e32 v21, s8
	ds_write_b32 v20, v21
.Lbgd_w0skip:
	v_sub_u32_e32 v6, 0, v5
	v_rcp_iflag_f32_e32 v7, v7
	v_add_u32_e32 v8, s0, v2
	v_mul_f32_e32 v7, 0x4f7ffffe, v7
	v_cvt_u32_f32_e32 v7, v7
	v_mul_lo_u32 v2, v6, v7
	v_mul_hi_u32 v2, v7, v2
	v_add_u32_e32 v2, v7, v2
	v_mul_hi_u32 v2, v8, v2
	v_mul_lo_u32 v6, v2, v5
	v_sub_u32_e32 v6, v8, v6
	v_add_u32_e32 v7, 1, v2
	v_cmp_ge_u32_e32 vcc, v6, v5
	s_nop 1
	v_cndmask_b32_e32 v2, v2, v7, vcc
	v_sub_u32_e32 v7, v6, v5
	v_cndmask_b32_e32 v6, v6, v7, vcc
	v_add_u32_e32 v7, 1, v2
	v_cmp_ge_u32_e32 vcc, v6, v5
	v_add_u32_e32 v6, 1, v8
	s_nop 0
	v_cndmask_b32_e32 v2, v2, v7, vcc
	v_mul_lo_u32 v7, v5, v2
	v_add_u32_e32 v5, v7, v5
	v_cmp_ne_u32_e32 vcc, v6, v5
	s_and_saveexec_b64 s[0:1], vcc
	s_xor_b64 s[0:1], exec, s[0:1]
	s_cbranch_execz .LBB0_735
	v_readlane_b32 s8, v253, 14
	v_readlane_b32 s9, v253, 15
	s_waitcnt lgkmcnt(0)
	s_nop 3
	buffer_inv sc1
	global_load_dword v4, v3, s[8:9] sc1
	s_waitcnt vmcnt(0)
	v_cmp_eq_u32_e32 vcc, v4, v2
	s_and_saveexec_b64 s[8:9], vcc
	s_cbranch_execz .LBB0_734
	s_mov_b32 s15, 1
	s_mov_b64 s[12:13], 0
	s_branch .LBB0_725

; __device__ __forceinline__ void xcd_barrier_cv(const XcdBarrier& b, Frame& F, const CvPtrs& P, int s, bool local) {
;     asm volatile("s_waitcnt vmcnt(0)" ::: "memory");
;     __syncthreads();
;     if (threadIdx.x < 64) { if (threadIdx.x == 0) { if (local) xcc_barrier_thread0(b); else xcd_barrier_thread0(b); } }
;     else if (cv_bg_share(s) >= 0 && cv_bg_share(s) < CV_BG_SHARES) cv_background(F, P, s);
;     __syncthreads();
; }
.LBB0_769:
	s_and_b64 vcc, exec, s[0:1]
	s_cbranch_vccz .LBB0_1015
	v_mov_b32_e32 v20, 0x20180
	s_movk_i32 s8, 16
	s_add_i32 s7, s89, 1
.Lbgd_loop:
	s_sleep 8
	ds_read_b32 v21, v20
	s_waitcnt lgkmcnt(0)
	v_readfirstlane_b32 s9, v21
	s_cmp_eq_u32 s9, s7
	s_cbranch_scc1 .Lbgd_go
	s_sub_u32 s8, s8, 1
	s_cmp_lg_u32 s8, 0
	s_cbranch_scc1 .Lbgd_loop
.Lbgd_go:
	v_mov_b32_e32 v4, v0
	s_mov_b64 s[6:7], -1
	v_readfirstlane_b32 s8, v4
	s_mov_b64 s[0:1], 0
	s_cmp_lt_i32 s89, 5
	s_mov_b64 s[4:5], 0
	s_cbranch_scc1 .LBB0_787
	s_cmp_gt_i32 s89, 7
	s_cbranch_scc0 .LBB0_779
	s_cmp_gt_i32 s89, 8
	s_cbranch_scc0 .LBB0_776
	s_cmp_eq_u32 s89, 9
	s_mov_b64 s[4:5], -1
	s_cbranch_scc0 .LBB0_775
	s_mov_b64 s[4:5], 0
